# v19 + L2 touch-prefetch of next-iteration rows in the first stream-copy loop
# baseline (speedup 1.0000x reference)
.LBB0_121:
	v_add_u32_e32 v38, s20, v40
	v_cmp_gt_i32_e64 s[4:5], s3, v38
	v_ashrrev_i32_e32 v39, 31, v38
	s_and_saveexec_b64 s[6:7], s[4:5]
	s_cbranch_execz .LBB0_123
	v_lshlrev_b64 v[2:3], 12, v[38:39]
	s_waitcnt lgkmcnt(0)
	v_lshl_add_u64 v[50:51], v[36:37], 0, v[2:3]
	global_load_dwordx4 v[22:25], v[50:51], off offset:16
	global_load_dwordx4 v[2:5], v[50:51], off
	global_load_dwordx4 v[26:29], v[50:51], off offset:2064
	global_load_dwordx4 v[30:33], v[50:51], off offset:2048
	v_mbcnt_lo_u32_b32 v60, -1, 0
	v_mbcnt_hi_u32_b32 v60, -1, v60
	v_lshrrev_b32_e32 v61, 5, v60
	s_mul_i32 s98, s20, 3
	v_mul_u32_u24_e32 v61, s20, v61
	v_add3_u32 v61, v40, s98, v61
	v_min_i32_e32 v61, 0x7fff, v61
	v_and_b32_e32 v62, 31, v60
	v_lshlrev_b32_e32 v62, 7, v62
	v_lshl_add_u32 v62, v61, 12, v62
	v_mov_b32_e32 v63, 0
	v_lshl_add_u64 v[62:63], s[36:37], 0, v[62:63]
	global_load_dword v64, v[62:63], off
	s_or_b64 exec, exec, s[6:7]
	s_waitcnt vmcnt(5) lgkmcnt(0)
	s_branch .Le00_p0

.LBB0_125:
	s_or_b64 exec, exec, s[14:15]
	s_and_saveexec_b64 s[6:7], s[4:5]
	s_cbranch_execz .LBB0_120
	v_add_u32_e32 v40, s18, v40
	v_cmp_gt_i32_e64 s[4:5], s3, v40
	s_and_saveexec_b64 s[14:15], s[4:5]
	s_cbranch_execz .LBB0_128
	v_ashrrev_i32_e32 v41, 31, v40
	v_lshlrev_b64 v[6:7], 12, v[40:41]
	v_lshl_add_u64 v[40:41], v[36:37], 0, v[6:7]
	global_load_dwordx4 v[10:13], v[40:41], off offset:16
	global_load_dwordx4 v[6:9], v[40:41], off
	global_load_dwordx4 v[18:21], v[40:41], off offset:2064
	global_load_dwordx4 v[14:17], v[40:41], off offset:2048
	s_or_b64 exec, exec, s[14:15]
	s_waitcnt vmcnt(8)
	s_branch .Le00_p1
